# g7 plus de-serialised loads in the even-layer mixer: DFT staging loads (4 issued together, counted vmcnt) and conv_rows 7 row loads issued up front
# speedup vs baseline: 1.0056x; 1.0056x over previous
; #define LAS __attribute__((address_space(3)))
; __device__ __forceinline__ void dft_item(LAS unsigned char* lds, const bf16_t* F, int KF, const bf16_t* X, int khalf, size_t segoff, size_t kstride, bf16_t* Ob, size_t ostride) {
;     ...
;     for (int kc = 0; kc < KF; kc += 128) {
;         __syncthreads();
; #pragma unroll
;         for (int i = 0; i < 4; ++i) {
;             const int c = tid + 512 * i, k = c >> 4, part = c & 15, kk = kc + k;
;             const u32x4 v = __builtin_nontemporal_load((const u32x4*)(X + (size_t)(kk / khalf) * segoff + (size_t)(kk % khalf) * kstride + part * 8));
;             LAS u32x2* d = (LAS u32x2*)(xs + k * LS + part * 8);
;             d[0] = (u32x2){v.x, v.y}; d[1] = (u32x2){v.z, v.w};
;         }
;         __syncthreads();
; #pragma unroll
;         for (int ks = 0; ks < 4; ++ks) {
;             const bf16x8 af = *(const bf16x8*)(F + (size_t)(16 * w + r16) * KF + kc + 32 * ks + 8 * kq);
; #pragma unroll
;             for (int nt = 0; nt < 8; ++nt) {
;                 LAS const bf16_t* xp = xs + (32 * ks + 8 * kq) * LS + 16 * nt + r16;
;                 bf16x8 bfr;
; #pragma unroll
;                 for (int j = 0; j < 8; ++j) bfr[j] = (short)xp[j * LS];
;                 acc[nt] = __builtin_amdgcn_mfma_f32_16x16x32_bf16(bfr, af, acc[nt], 0, 0, 0);
;             }
;         }
.LBB0_1143:
	s_and_b64 vcc, exec, s[8:9]
	s_cbranch_vccz .LBB0_1138
	s_bfe_u32 s15, s14, 0x70002
	s_ashr_i32 s8, s14, 9
	s_lshl_b32 s9, s15, 15
	s_add_u32 s20, s12, s9
	s_addc_u32 s21, s13, 0
	s_ashr_i32 s9, s8, 31
	s_lshl_b64 s[10:11], s[8:9], 13
	s_or_b32 s10, s10, s15
	s_mulk_i32 s11, 0x1400
	s_mul_hi_u32 s17, s10, 0x1400
	s_add_i32 s17, s17, s11
	s_mulk_i32 s10, 0x1400
	s_add_u32 s10, s4, s10
	s_addc_u32 s11, s5, s17
	s_lshl_b32 s16, s16, 1
	v_mov_b32_e32 v1, v194
	s_add_u32 s10, s10, s16
	s_addc_u32 s11, s11, 0
	v_ashrrev_i32_e32 v2, 2, v1
	s_lshl_b64 s[8:9], s[8:9], 24
	v_bfi_b32 v52, -16, v2, v1
	s_add_u32 s8, s2, s8
	v_ashrrev_i32_e32 v53, 31, v52
	s_addc_u32 s9, s3, s9
	s_lshl_b32 s15, s15, 10
	v_bfe_u32 v14, v1, 4, 2
	v_lshlrev_b32_e32 v0, 4, v1
	v_lshlrev_b64 v[2:3], 8, v[52:53]
	s_add_u32 s8, s8, s15
	v_and_b32_e32 v4, 0xf0, v0
	v_lshl_add_u64 v[2:3], s[20:21], 0, v[2:3]
	v_lshlrev_b32_e32 v6, 4, v14
	v_mov_b32_e32 v7, v145
	s_addc_u32 s9, s9, 0
	v_and_b32_e32 v5, 15, v1
	v_add_u32_e32 v0, 0, v4
	v_lshl_add_u64 v[54:55], v[2:3], 0, v[6:7]
	v_ashrrev_i32_e32 v3, 4, v1
	s_movk_i32 s15, 0x108
	s_add_u32 s8, s8, s16
	v_lshlrev_b32_e32 v2, 1, v5
	v_mad_u64_u32 v[6:7], s[16:17], v3, s15, v[0:1]
	v_add_u32_e32 v5, 0x200, v1
	v_ashrrev_i32_e32 v7, 4, v5
	v_mad_u64_u32 v[8:9], s[16:17], v7, s15, v[0:1]
	v_add_u32_e32 v5, 0x400, v1
	v_ashrrev_i32_e32 v9, 4, v5
	v_mad_u64_u32 v[10:11], s[16:17], v9, s15, v[0:1]
	v_add_u32_e32 v5, 0x600, v1
	v_ashrrev_i32_e32 v11, 4, v5
	v_mad_u64_u32 v[12:13], s[16:17], v11, s15, v[0:1]
	v_mul_u32_u24_e32 v0, 0x840, v14
	v_add3_u32 v56, 0, v2, v0
	v_ashrrev_i32_e32 v0, 31, v1
	v_lshrrev_b32_e32 v0, 26, v0
	v_add_u32_e32 v2, v3, v0
	v_ashrrev_i32_e32 v0, 6, v2
	v_and_b32_e32 v2, 0xffc0, v2
	v_ashrrev_i32_e32 v1, 31, v0
	v_sub_u32_e32 v2, v3, v2
	s_mov_b32 s15, 0x50000
	v_lshlrev_b64 v[0:1], 10, v[0:1]
	v_mul_lo_u32 v2, v2, s15
	v_lshl_add_u64 v[0:1], s[10:11], 0, v[0:1]
	v_ashrrev_i32_e32 v3, 31, v2
	v_lshl_add_u64 v[0:1], v[2:3], 1, v[0:1]
	v_mov_b32_e32 v5, v145
	v_lshl_add_u64 v[0:1], v[0:1], 0, v[4:5]
	s_barrier
	global_load_dwordx4 v[96:99], v[0:1], off offset:3072 nt
	v_lshlrev_b32_e32 v144, 3, v14
	s_addc_u32 s9, s9, 0
	v_ashrrev_i32_e32 v0, 31, v7
	v_lshrrev_b32_e32 v0, 26, v0
	v_add_u32_e32 v2, v7, v0
	v_ashrrev_i32_e32 v0, 6, v2
	v_and_b32_e32 v2, 0xffc0, v2
	v_ashrrev_i32_e32 v1, 31, v0
	v_sub_u32_e32 v2, v7, v2
	v_lshlrev_b64 v[0:1], 10, v[0:1]
	v_mul_lo_u32 v2, v2, s15
	v_lshl_add_u64 v[0:1], s[10:11], 0, v[0:1]
	v_ashrrev_i32_e32 v3, 31, v2
	v_lshl_add_u64 v[0:1], v[2:3], 1, v[0:1]
	v_lshl_add_u64 v[0:1], v[0:1], 0, v[4:5]
	global_load_dwordx4 v[100:103], v[0:1], off offset:3072 nt
	v_ashrrev_i32_e32 v0, 31, v9
	v_lshrrev_b32_e32 v0, 26, v0
	v_add_u32_e32 v2, v9, v0
	v_ashrrev_i32_e32 v0, 6, v2
	v_and_b32_e32 v2, 0xffc0, v2
	v_ashrrev_i32_e32 v1, 31, v0
	v_sub_u32_e32 v2, v9, v2
	v_lshlrev_b64 v[0:1], 10, v[0:1]
	v_mul_lo_u32 v2, v2, s15
	v_lshl_add_u64 v[0:1], s[10:11], 0, v[0:1]
	v_ashrrev_i32_e32 v3, 31, v2
	v_lshl_add_u64 v[0:1], v[2:3], 1, v[0:1]
	v_lshl_add_u64 v[0:1], v[0:1], 0, v[4:5]
	global_load_dwordx4 v[104:107], v[0:1], off offset:3072 nt
	v_ashrrev_i32_e32 v0, 31, v11
	v_lshrrev_b32_e32 v0, 26, v0
	v_add_u32_e32 v2, v11, v0
	v_ashrrev_i32_e32 v0, 6, v2
	v_and_b32_e32 v2, 0xffc0, v2
	v_ashrrev_i32_e32 v1, 31, v0
	v_sub_u32_e32 v2, v11, v2
	v_lshlrev_b64 v[0:1], 10, v[0:1]
	v_mul_lo_u32 v2, v2, s15
	v_lshl_add_u64 v[0:1], s[10:11], 0, v[0:1]
	v_ashrrev_i32_e32 v3, 31, v2
	v_lshl_add_u64 v[0:1], v[2:3], 1, v[0:1]
	v_lshl_add_u64 v[0:1], v[0:1], 0, v[4:5]
	global_load_dwordx4 v[108:111], v[0:1], off offset:3072 nt
	s_waitcnt vmcnt(3)
	ds_write2_b64 v6, v[96:97], v[98:99] offset1:1
	s_waitcnt vmcnt(2)
	ds_write2_b64 v8, v[100:101], v[102:103] offset1:1
	s_waitcnt vmcnt(1)
	ds_write2_b64 v10, v[104:105], v[106:107] offset1:1
	s_waitcnt vmcnt(0)
	ds_write2_b64 v12, v[108:109], v[110:111] offset1:1
	s_waitcnt lgkmcnt(0)
	s_barrier
	global_load_dwordx4 v[0:3], v[54:55], off
	ds_read_u16 v4, v56 offset:264
	ds_read_u16 v5, v56 offset:528
	ds_read_u16 v8, v56 offset:792
	ds_read_u16 v6, v56 offset:1056
	ds_read_u16 v9, v56 offset:1320
	ds_read_u16 v7, v56 offset:1584
	ds_read_u16 v10, v56 offset:1848
	s_waitcnt lgkmcnt(4)
	v_perm_b32 v5, v8, v5, s73
	s_waitcnt lgkmcnt(2)
	v_perm_b32 v6, v9, v6, s73
	ds_read_u16 v8, v56
	ds_read_u16 v9, v56 offset:32
	s_waitcnt lgkmcnt(2)
	v_perm_b32 v7, v10, v7, s73
	s_waitcnt lgkmcnt(1)
	v_perm_b32 v4, v4, v8, s73
	s_waitcnt vmcnt(0)
	s_nop 0
	v_mfma_f32_16x16x32_bf16 v[16:19], v[4:7], v[0:3], 0
	ds_read_u16 v4, v56 offset:296
	ds_read_u16 v5, v56 offset:560
	ds_read_u16 v8, v56 offset:824
	ds_read_u16 v6, v56 offset:1088
	ds_read_u16 v10, v56 offset:1352
	ds_read_u16 v7, v56 offset:1616
	ds_read_u16 v11, v56 offset:1880
	s_waitcnt lgkmcnt(4)
	v_perm_b32 v5, v8, v5, s73
	v_perm_b32 v4, v4, v9, s73
	s_waitcnt lgkmcnt(2)
	v_perm_b32 v6, v10, v6, s73
	s_waitcnt lgkmcnt(0)
	v_perm_b32 v7, v11, v7, s73
	s_nop 1
	v_mfma_f32_16x16x32_bf16 v[12:15], v[4:7], v[0:3], 0
	ds_read_u16 v4, v56 offset:64
	ds_read_u16 v8, v56 offset:328
	ds_read_u16 v5, v56 offset:592
	ds_read_u16 v9, v56 offset:856
	ds_read_u16 v6, v56 offset:1120
	ds_read_u16 v10, v56 offset:1384
	ds_read_u16 v7, v56 offset:1648
	ds_read_u16 v11, v56 offset:1912
	s_waitcnt lgkmcnt(4)
	v_perm_b32 v5, v9, v5, s73
	v_perm_b32 v4, v8, v4, s73
	s_waitcnt lgkmcnt(2)
	v_perm_b32 v6, v10, v6, s73
	s_waitcnt lgkmcnt(0)
	v_perm_b32 v7, v11, v7, s73
	s_nop 1
	v_mfma_f32_16x16x32_bf16 v[8:11], v[4:7], v[0:3], 0
	ds_read_u16 v4, v56 offset:96
	ds_read_u16 v20, v56 offset:360
	ds_read_u16 v5, v56 offset:624
	ds_read_u16 v21, v56 offset:888
	ds_read_u16 v6, v56 offset:1152
	ds_read_u16 v22, v56 offset:1416
	ds_read_u16 v7, v56 offset:1680
	ds_read_u16 v23, v56 offset:1944
	s_waitcnt lgkmcnt(4)
; #define LAS __attribute__((address_space(3)))
; __device__ __forceinline__ void dft_item(LAS unsigned char* lds, const bf16_t* F, int KF, const bf16_t* X, int khalf, size_t segoff, size_t kstride, bf16_t* Ob, size_t ostride) {
;     ...
; #pragma unroll
;         for (int ks = 0; ks < 4; ++ks) {
;             const bf16x8 af = *(const bf16x8*)(F + (size_t)(16 * w + r16) * KF + kc + 32 * ks + 8 * kq);
; #pragma unroll
;             for (int nt = 0; nt < 8; ++nt) {
;                 LAS const bf16_t* xp = xs + (32 * ks + 8 * kq) * LS + 16 * nt + r16;
;                 bf16x8 bfr;
; #pragma unroll
;                 for (int j = 0; j < 8; ++j) bfr[j] = (short)xp[j * LS];
;                 acc[nt] = __builtin_amdgcn_mfma_f32_16x16x32_bf16(bfr, af, acc[nt], 0, 0, 0);
;             }
;         }
	v_perm_b32 v5, v21, v5, s73
	v_perm_b32 v4, v20, v4, s73
	s_waitcnt lgkmcnt(2)
	v_perm_b32 v6, v22, v6, s73
	s_waitcnt lgkmcnt(0)
	v_perm_b32 v7, v23, v7, s73
	ds_read_u16 v20, v56 offset:128
	ds_read_u16 v24, v56 offset:392
	ds_read_u16 v21, v56 offset:656
	ds_read_u16 v25, v56 offset:920
	ds_read_u16 v22, v56 offset:1184
	ds_read_u16 v26, v56 offset:1448
	ds_read_u16 v23, v56 offset:1712
	ds_read_u16 v27, v56 offset:1976
	s_waitcnt lgkmcnt(4)
	v_perm_b32 v21, v25, v21, s73
	v_perm_b32 v20, v24, v20, s73
	s_waitcnt lgkmcnt(2)
	v_perm_b32 v22, v26, v22, s73
	v_mfma_f32_16x16x32_bf16 v[4:7], v[4:7], v[0:3], 0
	s_waitcnt lgkmcnt(0)
	v_perm_b32 v23, v27, v23, s73
	ds_read_u16 v24, v56 offset:160
	ds_read_u16 v28, v56 offset:424
	ds_read_u16 v25, v56 offset:688
	ds_read_u16 v29, v56 offset:952
	ds_read_u16 v26, v56 offset:1216
	ds_read_u16 v30, v56 offset:1480
	ds_read_u16 v27, v56 offset:1744
	ds_read_u16 v31, v56 offset:2008
	s_waitcnt lgkmcnt(4)
	v_perm_b32 v25, v29, v25, s73
	v_perm_b32 v24, v28, v24, s73
	s_waitcnt lgkmcnt(2)
	v_perm_b32 v26, v30, v26, s73
	v_mfma_f32_16x16x32_bf16 v[20:23], v[20:23], v[0:3], 0
	s_waitcnt lgkmcnt(0)
	v_perm_b32 v27, v31, v27, s73
	ds_read_u16 v28, v56 offset:192
	ds_read_u16 v32, v56 offset:456
	ds_read_u16 v29, v56 offset:720
	ds_read_u16 v33, v56 offset:984
	ds_read_u16 v30, v56 offset:1248
	ds_read_u16 v34, v56 offset:1512
	ds_read_u16 v31, v56 offset:1776
	ds_read_u16 v35, v56 offset:2040
	s_waitcnt lgkmcnt(4)
	v_perm_b32 v29, v33, v29, s73
	v_perm_b32 v28, v32, v28, s73
	s_waitcnt lgkmcnt(2)
	v_perm_b32 v30, v34, v30, s73
	v_mfma_f32_16x16x32_bf16 v[24:27], v[24:27], v[0:3], 0
	s_waitcnt lgkmcnt(0)
	v_perm_b32 v31, v35, v31, s73
	ds_read_u16 v32, v56 offset:224
	ds_read_u16 v36, v56 offset:488
	ds_read_u16 v33, v56 offset:752
	ds_read_u16 v37, v56 offset:1016
	ds_read_u16 v34, v56 offset:1280
	ds_read_u16 v38, v56 offset:1544
	ds_read_u16 v35, v56 offset:1808
	ds_read_u16 v39, v56 offset:2072
	s_waitcnt lgkmcnt(4)
	v_perm_b32 v33, v37, v33, s73
	v_perm_b32 v32, v36, v32, s73
	s_waitcnt lgkmcnt(2)
	v_perm_b32 v34, v38, v34, s73
	v_mfma_f32_16x16x32_bf16 v[28:31], v[28:31], v[0:3], 0
	s_waitcnt lgkmcnt(0)
	v_perm_b32 v35, v39, v35, s73
	s_nop 1
	v_mfma_f32_16x16x32_bf16 v[0:3], v[32:35], v[0:3], 0
	global_load_dwordx4 v[32:35], v[54:55], off offset:64
	ds_read_u16 v36, v56 offset:8448
	ds_read_u16 v40, v56 offset:8712
	ds_read_u16 v37, v56 offset:8976
	ds_read_u16 v41, v56 offset:9240
	ds_read_u16 v38, v56 offset:9504
	ds_read_u16 v42, v56 offset:9768
	ds_read_u16 v39, v56 offset:10032
	ds_read_u16 v43, v56 offset:10296
	s_waitcnt lgkmcnt(4)
	v_perm_b32 v37, v41, v37, s73
	v_perm_b32 v36, v40, v36, s73
	s_waitcnt lgkmcnt(2)
	v_perm_b32 v38, v42, v38, s73
	s_waitcnt lgkmcnt(0)
	v_perm_b32 v39, v43, v39, s73
	s_waitcnt vmcnt(0)
	s_nop 0
	v_mfma_f32_16x16x32_bf16 v[16:19], v[36:39], v[32:35], v[16:19]
	ds_read_u16 v36, v56 offset:8480
	ds_read_u16 v40, v56 offset:8744
	ds_read_u16 v37, v56 offset:9008
	ds_read_u16 v41, v56 offset:9272
	ds_read_u16 v38, v56 offset:9536
	ds_read_u16 v42, v56 offset:9800
	ds_read_u16 v39, v56 offset:10064
	ds_read_u16 v43, v56 offset:10328
	s_waitcnt lgkmcnt(4)
	v_perm_b32 v37, v41, v37, s73
	v_perm_b32 v36, v40, v36, s73
	s_waitcnt lgkmcnt(2)
	v_perm_b32 v38, v42, v38, s73
	s_waitcnt lgkmcnt(0)
	v_perm_b32 v39, v43, v39, s73
	s_nop 1
	v_mfma_f32_16x16x32_bf16 v[12:15], v[36:39], v[32:35], v[12:15]
	ds_read_u16 v36, v56 offset:8512
	ds_read_u16 v40, v56 offset:8776
	ds_read_u16 v37, v56 offset:9040
	ds_read_u16 v41, v56 offset:9304
	ds_read_u16 v38, v56 offset:9568
	ds_read_u16 v42, v56 offset:9832
	ds_read_u16 v39, v56 offset:10096
	ds_read_u16 v43, v56 offset:10360
	s_waitcnt lgkmcnt(4)
	v_perm_b32 v37, v41, v37, s73
	v_perm_b32 v36, v40, v36, s73
	s_waitcnt lgkmcnt(2)
	v_perm_b32 v38, v42, v38, s73
	s_waitcnt lgkmcnt(0)
	v_perm_b32 v39, v43, v39, s73
	s_nop 1
	v_mfma_f32_16x16x32_bf16 v[8:11], v[36:39], v[32:35], v[8:11]
	ds_read_u16 v36, v56 offset:8544
	ds_read_u16 v40, v56 offset:8808
	ds_read_u16 v37, v56 offset:9072
	ds_read_u16 v41, v56 offset:9336
	ds_read_u16 v38, v56 offset:9600
	ds_read_u16 v42, v56 offset:9864
	ds_read_u16 v39, v56 offset:10128
	ds_read_u16 v43, v56 offset:10392
	s_waitcnt lgkmcnt(4)
	v_perm_b32 v37, v41, v37, s73
	v_perm_b32 v36, v40, v36, s73
	s_waitcnt lgkmcnt(2)
	v_perm_b32 v38, v42, v38, s73
	s_waitcnt lgkmcnt(0)
	v_perm_b32 v39, v43, v39, s73
	s_nop 1
	v_mfma_f32_16x16x32_bf16 v[4:7], v[36:39], v[32:35], v[4:7]
	ds_read_u16 v36, v56 offset:8576
	ds_read_u16 v40, v56 offset:8840
	ds_read_u16 v37, v56 offset:9104
	ds_read_u16 v41, v56 offset:9368
	ds_read_u16 v38, v56 offset:9632
	ds_read_u16 v42, v56 offset:9896
	ds_read_u16 v39, v56 offset:10160
	ds_read_u16 v43, v56 offset:10424
	s_waitcnt lgkmcnt(4)
	v_perm_b32 v37, v41, v37, s73
	v_perm_b32 v36, v40, v36, s73
	s_waitcnt lgkmcnt(2)
	v_perm_b32 v38, v42, v38, s73
	s_waitcnt lgkmcnt(0)
	v_perm_b32 v39, v43, v39, s73
	s_nop 1
	v_mfma_f32_16x16x32_bf16 v[36:39], v[36:39], v[32:35], v[20:23]
	s_nop 2
	ds_read_u16 v20, v56 offset:8608
	ds_read_u16 v40, v56 offset:8872
	ds_read_u16 v21, v56 offset:9136
	ds_read_u16 v41, v56 offset:9400
	ds_read_u16 v22, v56 offset:9664
	ds_read_u16 v42, v56 offset:9928
	ds_read_u16 v23, v56 offset:10192
	ds_read_u16 v43, v56 offset:10456
	s_waitcnt lgkmcnt(4)
	v_perm_b32 v21, v41, v21, s73
	v_perm_b32 v20, v40, v20, s73
	s_waitcnt lgkmcnt(2)
	v_perm_b32 v22, v42, v22, s73
	s_waitcnt lgkmcnt(0)
; #define LAS __attribute__((address_space(3)))
; __device__ __forceinline__ void dft_item(LAS unsigned char* lds, const bf16_t* F, int KF, const bf16_t* X, int khalf, size_t segoff, size_t kstride, bf16_t* Ob, size_t ostride) {
;     ...
; #pragma unroll
;         for (int ks = 0; ks < 4; ++ks) {
;             const bf16x8 af = *(const bf16x8*)(F + (size_t)(16 * w + r16) * KF + kc + 32 * ks + 8 * kq);
; #pragma unroll
;             for (int nt = 0; nt < 8; ++nt) {
;                 LAS const bf16_t* xp = xs + (32 * ks + 8 * kq) * LS + 16 * nt + r16;
;                 bf16x8 bfr;
; #pragma unroll
;                 for (int j = 0; j < 8; ++j) bfr[j] = (short)xp[j * LS];
;                 acc[nt] = __builtin_amdgcn_mfma_f32_16x16x32_bf16(bfr, af, acc[nt], 0, 0, 0);
;             }
;         }
	v_perm_b32 v23, v43, v23, s73
	s_nop 1
	v_mfma_f32_16x16x32_bf16 v[40:43], v[20:23], v[32:35], v[24:27]
	ds_read_u16 v20, v56 offset:8640
	s_nop 1
	ds_read_u16 v24, v56 offset:8904
	ds_read_u16 v21, v56 offset:9168
	ds_read_u16 v25, v56 offset:9432
	ds_read_u16 v22, v56 offset:9696
	ds_read_u16 v26, v56 offset:9960
	ds_read_u16 v23, v56 offset:10224
	ds_read_u16 v27, v56 offset:10488
	s_waitcnt lgkmcnt(4)
	v_perm_b32 v21, v25, v21, s73
	v_perm_b32 v20, v24, v20, s73
	s_waitcnt lgkmcnt(2)
	v_perm_b32 v22, v26, v22, s73
	s_waitcnt lgkmcnt(0)
	v_perm_b32 v23, v27, v23, s73
	s_nop 1
	v_mfma_f32_16x16x32_bf16 v[44:47], v[20:23], v[32:35], v[28:31]
	ds_read_u16 v20, v56 offset:8672
	ds_read_u16 v24, v56 offset:8936
	ds_read_u16 v21, v56 offset:9200
	ds_read_u16 v25, v56 offset:9464
	ds_read_u16 v22, v56 offset:9728
	ds_read_u16 v26, v56 offset:9992
	ds_read_u16 v23, v56 offset:10256
	ds_read_u16 v27, v56 offset:10520
	global_load_dwordx4 v[48:51], v[54:55], off offset:128
	s_waitcnt lgkmcnt(4)
	v_perm_b32 v21, v25, v21, s73
	s_waitcnt lgkmcnt(2)
	v_perm_b32 v22, v26, v22, s73
	v_perm_b32 v20, v24, v20, s73
	s_waitcnt lgkmcnt(0)
	v_perm_b32 v23, v27, v23, s73
	s_nop 1
	v_mfma_f32_16x16x32_bf16 v[0:3], v[20:23], v[32:35], v[0:3]
	ds_read_u16 v20, v56 offset:16896
	ds_read_u16 v24, v56 offset:17160
	ds_read_u16 v21, v56 offset:17424
	ds_read_u16 v25, v56 offset:17688
	ds_read_u16 v22, v56 offset:17952
	ds_read_u16 v26, v56 offset:18216
	ds_read_u16 v23, v56 offset:18480
	ds_read_u16 v27, v56 offset:18744
	s_waitcnt lgkmcnt(4)
	v_perm_b32 v21, v25, v21, s73
	v_perm_b32 v20, v24, v20, s73
	s_waitcnt lgkmcnt(2)
	v_perm_b32 v22, v26, v22, s73
	s_waitcnt lgkmcnt(0)
	v_perm_b32 v23, v27, v23, s73
	s_waitcnt vmcnt(0)
	s_nop 0
	v_mfma_f32_16x16x32_bf16 v[24:27], v[20:23], v[48:51], v[16:19]
	s_nop 2
	ds_read_u16 v16, v56 offset:16928
	ds_read_u16 v20, v56 offset:17192
	ds_read_u16 v17, v56 offset:17456
	ds_read_u16 v21, v56 offset:17720
	ds_read_u16 v18, v56 offset:17984
	ds_read_u16 v22, v56 offset:18248
	ds_read_u16 v19, v56 offset:18512
	ds_read_u16 v23, v56 offset:18776
	s_waitcnt lgkmcnt(4)
	v_perm_b32 v17, v21, v17, s73
	v_perm_b32 v16, v20, v16, s73
	s_waitcnt lgkmcnt(2)
	v_perm_b32 v18, v22, v18, s73
	s_waitcnt lgkmcnt(0)
	v_perm_b32 v19, v23, v19, s73
	s_nop 1
	v_mfma_f32_16x16x32_bf16 v[28:31], v[16:19], v[48:51], v[12:15]
	s_nop 2
	ds_read_u16 v12, v56 offset:16960
	ds_read_u16 v16, v56 offset:17224
	ds_read_u16 v13, v56 offset:17488
	ds_read_u16 v17, v56 offset:17752
	ds_read_u16 v14, v56 offset:18016
	ds_read_u16 v18, v56 offset:18280
	ds_read_u16 v15, v56 offset:18544
	ds_read_u16 v19, v56 offset:18808
	s_waitcnt lgkmcnt(4)
	v_perm_b32 v13, v17, v13, s73
	v_perm_b32 v12, v16, v12, s73
	s_waitcnt lgkmcnt(2)
	v_perm_b32 v14, v18, v14, s73
	s_waitcnt lgkmcnt(0)
	v_perm_b32 v15, v19, v15, s73
	s_nop 1
	v_mfma_f32_16x16x32_bf16 v[32:35], v[12:15], v[48:51], v[8:11]
	s_nop 2
	ds_read_u16 v8, v56 offset:16992
	ds_read_u16 v12, v56 offset:17256
	ds_read_u16 v9, v56 offset:17520
	ds_read_u16 v13, v56 offset:17784
	ds_read_u16 v10, v56 offset:18048
	ds_read_u16 v14, v56 offset:18312
	ds_read_u16 v11, v56 offset:18576
	ds_read_u16 v15, v56 offset:18840
	s_waitcnt lgkmcnt(4)
	v_perm_b32 v9, v13, v9, s73
	v_perm_b32 v8, v12, v8, s73
	s_waitcnt lgkmcnt(2)
	v_perm_b32 v10, v14, v10, s73
	s_waitcnt lgkmcnt(0)
	v_perm_b32 v11, v15, v11, s73
	s_nop 1
	v_mfma_f32_16x16x32_bf16 v[20:23], v[8:11], v[48:51], v[4:7]
	s_nop 2
	ds_read_u16 v4, v56 offset:17024
	ds_read_u16 v8, v56 offset:17288
	ds_read_u16 v5, v56 offset:17552
	ds_read_u16 v9, v56 offset:17816
	ds_read_u16 v6, v56 offset:18080
	ds_read_u16 v10, v56 offset:18344
	ds_read_u16 v7, v56 offset:18608
	ds_read_u16 v11, v56 offset:18872
	s_waitcnt lgkmcnt(4)
	v_perm_b32 v5, v9, v5, s73
	v_perm_b32 v4, v8, v4, s73
	s_waitcnt lgkmcnt(2)
	v_perm_b32 v6, v10, v6, s73
	s_waitcnt lgkmcnt(0)
	v_perm_b32 v7, v11, v7, s73
	s_nop 1
	v_mfma_f32_16x16x32_bf16 v[16:19], v[4:7], v[48:51], v[36:39]
	ds_read_u16 v4, v56 offset:17056
	ds_read_u16 v8, v56 offset:17320
	ds_read_u16 v5, v56 offset:17584
	ds_read_u16 v9, v56 offset:17848
	ds_read_u16 v6, v56 offset:18112
	ds_read_u16 v10, v56 offset:18376
	ds_read_u16 v7, v56 offset:18640
	ds_read_u16 v11, v56 offset:18904
	s_waitcnt lgkmcnt(4)
	v_perm_b32 v5, v9, v5, s73
	v_perm_b32 v4, v8, v4, s73
	s_waitcnt lgkmcnt(2)
	v_perm_b32 v6, v10, v6, s73
	s_waitcnt lgkmcnt(0)
	v_perm_b32 v7, v11, v7, s73
	s_nop 1
	v_mfma_f32_16x16x32_bf16 v[12:15], v[4:7], v[48:51], v[40:43]
	ds_read_u16 v4, v56 offset:17088
	ds_read_u16 v8, v56 offset:17352
	ds_read_u16 v5, v56 offset:17616
	ds_read_u16 v9, v56 offset:17880
	ds_read_u16 v6, v56 offset:18144
	ds_read_u16 v10, v56 offset:18408
	ds_read_u16 v7, v56 offset:18672
	ds_read_u16 v11, v56 offset:18936
	s_waitcnt lgkmcnt(4)
	v_perm_b32 v5, v9, v5, s73
	v_perm_b32 v4, v8, v4, s73
	s_waitcnt lgkmcnt(2)
	v_perm_b32 v6, v10, v6, s73
	s_waitcnt lgkmcnt(0)
	v_perm_b32 v7, v11, v7, s73
	s_nop 1
	v_mfma_f32_16x16x32_bf16 v[8:11], v[4:7], v[48:51], v[44:47]
	ds_read_u16 v4, v56 offset:17120
	ds_read_u16 v36, v56 offset:17384
	ds_read_u16 v5, v56 offset:17648
	ds_read_u16 v37, v56 offset:17912
	ds_read_u16 v6, v56 offset:18176
	ds_read_u16 v38, v56 offset:18440
	ds_read_u16 v7, v56 offset:18704
	ds_read_u16 v39, v56 offset:18968
	s_waitcnt lgkmcnt(4)
	v_perm_b32 v5, v37, v5, s73
	v_perm_b32 v4, v36, v4, s73
	s_waitcnt lgkmcnt(2)
	v_perm_b32 v6, v38, v6, s73
	s_waitcnt lgkmcnt(0)
; #define LAS __attribute__((address_space(3)))
; __device__ __forceinline__ unsigned pk2(float lo, float hi) { unsigned r; asm("v_cvt_pk_bf16_f32 %0, %1, %2" : "=v"(r) : "v"(lo), "v"(hi)); return r; }
; __device__ __forceinline__ void dft_item(LAS unsigned char* lds, const bf16_t* F, int KF, const bf16_t* X, int khalf, size_t segoff, size_t kstride, bf16_t* Ob, size_t ostride) {
;     ...
; #pragma unroll
;         for (int ks = 0; ks < 4; ++ks) {
;             const bf16x8 af = *(const bf16x8*)(F + (size_t)(16 * w + r16) * KF + kc + 32 * ks + 8 * kq);
; #pragma unroll
;             for (int nt = 0; nt < 8; ++nt) {
;                 LAS const bf16_t* xp = xs + (32 * ks + 8 * kq) * LS + 16 * nt + r16;
;                 bf16x8 bfr;
; #pragma unroll
;                 for (int j = 0; j < 8; ++j) bfr[j] = (short)xp[j * LS];
;                 acc[nt] = __builtin_amdgcn_mfma_f32_16x16x32_bf16(bfr, af, acc[nt], 0, 0, 0);
;             }
;         }
;     }
; #pragma unroll
;     for (int nt = 0; nt < 8; ++nt) {
;         const f32x4 v = acc[nt] + 0.f;
;         u32x2 o; o.x = pk2(v[0], v[1]); o.y = pk2(v[2], v[3]);
;         *(u32x2*)(Ob + (size_t)(16 * w + r16) * ostride + 16 * nt + 4 * kq) = o;
;     }
	v_perm_b32 v7, v39, v7, s73
	s_nop 1
	v_mfma_f32_16x16x32_bf16 v[0:3], v[4:7], v[48:51], v[0:3]
	global_load_dwordx4 v[4:7], v[54:55], off offset:192
	ds_read_u16 v36, v56 offset:25344
	ds_read_u16 v40, v56 offset:25608
	ds_read_u16 v37, v56 offset:25872
	ds_read_u16 v41, v56 offset:26136
	ds_read_u16 v38, v56 offset:26400
	ds_read_u16 v42, v56 offset:26664
	ds_read_u16 v39, v56 offset:26928
	ds_read_u16 v43, v56 offset:27192
	s_waitcnt lgkmcnt(4)
	v_perm_b32 v37, v41, v37, s73
	v_perm_b32 v36, v40, v36, s73
	s_waitcnt lgkmcnt(2)
	v_perm_b32 v38, v42, v38, s73
	s_waitcnt lgkmcnt(0)
	v_perm_b32 v39, v43, v39, s73
	s_waitcnt vmcnt(0)
	s_nop 0
	v_mfma_f32_16x16x32_bf16 v[24:27], v[36:39], v[4:7], v[24:27]
	ds_read_u16 v36, v56 offset:25376
	ds_read_u16 v40, v56 offset:25640
	ds_read_u16 v37, v56 offset:25904
	ds_read_u16 v41, v56 offset:26168
	ds_read_u16 v38, v56 offset:26432
	ds_read_u16 v42, v56 offset:26696
	ds_read_u16 v39, v56 offset:26960
	ds_read_u16 v43, v56 offset:27224
	s_waitcnt lgkmcnt(4)
	v_perm_b32 v37, v41, v37, s73
	v_perm_b32 v36, v40, v36, s73
	s_waitcnt lgkmcnt(2)
	v_perm_b32 v38, v42, v38, s73
	s_waitcnt lgkmcnt(0)
	v_perm_b32 v39, v43, v39, s73
	s_nop 1
	v_mfma_f32_16x16x32_bf16 v[28:31], v[36:39], v[4:7], v[28:31]
	ds_read_u16 v36, v56 offset:25408
	ds_read_u16 v40, v56 offset:25672
	ds_read_u16 v37, v56 offset:25936
	ds_read_u16 v41, v56 offset:26200
	ds_read_u16 v38, v56 offset:26464
	ds_read_u16 v42, v56 offset:26728
	ds_read_u16 v39, v56 offset:26992
	ds_read_u16 v43, v56 offset:27256
	s_waitcnt lgkmcnt(4)
	v_perm_b32 v37, v41, v37, s73
	v_perm_b32 v36, v40, v36, s73
	s_waitcnt lgkmcnt(2)
	v_perm_b32 v38, v42, v38, s73
	s_waitcnt lgkmcnt(0)
	v_perm_b32 v39, v43, v39, s73
	s_nop 1
	v_mfma_f32_16x16x32_bf16 v[32:35], v[36:39], v[4:7], v[32:35]
	ds_read_u16 v36, v56 offset:25440
	ds_read_u16 v40, v56 offset:25704
	ds_read_u16 v37, v56 offset:25968
	ds_read_u16 v41, v56 offset:26232
	ds_read_u16 v38, v56 offset:26496
	ds_read_u16 v42, v56 offset:26760
	ds_read_u16 v39, v56 offset:27024
	ds_read_u16 v43, v56 offset:27288
	s_waitcnt lgkmcnt(4)
	v_perm_b32 v37, v41, v37, s73
	v_perm_b32 v36, v40, v36, s73
	s_waitcnt lgkmcnt(2)
	v_perm_b32 v38, v42, v38, s73
	s_waitcnt lgkmcnt(0)
	v_perm_b32 v39, v43, v39, s73
	s_nop 1
	v_mfma_f32_16x16x32_bf16 v[20:23], v[36:39], v[4:7], v[20:23]
	ds_read_u16 v36, v56 offset:25472
	ds_read_u16 v40, v56 offset:25736
	ds_read_u16 v37, v56 offset:26000
	ds_read_u16 v41, v56 offset:26264
	ds_read_u16 v38, v56 offset:26528
	ds_read_u16 v42, v56 offset:26792
	ds_read_u16 v39, v56 offset:27056
	ds_read_u16 v43, v56 offset:27320
	s_waitcnt lgkmcnt(4)
	v_perm_b32 v37, v41, v37, s73
	v_perm_b32 v36, v40, v36, s73
	s_waitcnt lgkmcnt(2)
	v_perm_b32 v38, v42, v38, s73
	s_waitcnt lgkmcnt(0)
	v_perm_b32 v39, v43, v39, s73
	s_nop 1
	v_mfma_f32_16x16x32_bf16 v[16:19], v[36:39], v[4:7], v[16:19]
	ds_read_u16 v36, v56 offset:25504
	ds_read_u16 v40, v56 offset:25768
	ds_read_u16 v37, v56 offset:26032
	ds_read_u16 v41, v56 offset:26296
	ds_read_u16 v38, v56 offset:26560
	ds_read_u16 v42, v56 offset:26824
	ds_read_u16 v39, v56 offset:27088
	ds_read_u16 v43, v56 offset:27352
	s_waitcnt lgkmcnt(4)
	v_perm_b32 v37, v41, v37, s73
	v_perm_b32 v36, v40, v36, s73
	s_waitcnt lgkmcnt(2)
	v_perm_b32 v38, v42, v38, s73
	s_waitcnt lgkmcnt(0)
	v_perm_b32 v39, v43, v39, s73
	s_nop 1
	v_mfma_f32_16x16x32_bf16 v[12:15], v[36:39], v[4:7], v[12:15]
	ds_read_u16 v36, v56 offset:25536
	ds_read_u16 v40, v56 offset:25800
	ds_read_u16 v37, v56 offset:26064
	ds_read_u16 v41, v56 offset:26328
	ds_read_u16 v38, v56 offset:26592
	ds_read_u16 v42, v56 offset:26856
	ds_read_u16 v39, v56 offset:27120
	ds_read_u16 v43, v56 offset:27384
	s_waitcnt lgkmcnt(4)
	v_perm_b32 v37, v41, v37, s73
	v_perm_b32 v36, v40, v36, s73
	s_waitcnt lgkmcnt(2)
	v_perm_b32 v38, v42, v38, s73
	s_waitcnt lgkmcnt(0)
	v_perm_b32 v39, v43, v39, s73
	s_nop 1
	v_mfma_f32_16x16x32_bf16 v[8:11], v[36:39], v[4:7], v[8:11]
	ds_read_u16 v36, v56 offset:25568
	ds_read_u16 v40, v56 offset:25832
	ds_read_u16 v37, v56 offset:26096
	ds_read_u16 v41, v56 offset:26360
	ds_read_u16 v38, v56 offset:26624
	ds_read_u16 v42, v56 offset:26888
	ds_read_u16 v39, v56 offset:27152
	ds_read_u16 v43, v56 offset:27416
	s_waitcnt lgkmcnt(4)
	v_perm_b32 v37, v41, v37, s73
	v_perm_b32 v36, v40, v36, s73
	s_waitcnt lgkmcnt(2)
	v_perm_b32 v38, v42, v38, s73
	s_waitcnt lgkmcnt(0)
	v_perm_b32 v39, v43, v39, s73
	s_nop 1
	v_mfma_f32_16x16x32_bf16 v[0:3], v[36:39], v[4:7], v[0:3]
	v_lshlrev_b64 v[4:5], 17, v[52:53]
	v_lshl_add_u64 v[4:5], s[8:9], 0, v[4:5]
	v_pk_add_f32 v[6:7], v[24:25], 0 op_sel_hi:[1,0]
	v_lshl_add_u64 v[36:37], v[4:5], 0, v[144:145]
	v_pk_add_f32 v[4:5], v[26:27], 0 op_sel_hi:[1,0]
	v_cvt_pk_bf16_f32 v6, v6, v7
	s_nop 2
	v_pk_add_f32 v[0:1], v[0:1], 0 op_sel_hi:[1,0]
	v_cvt_pk_bf16_f32 v7, v4, v5
	global_store_dwordx2 v[36:37], v[6:7], off
	v_pk_add_f32 v[6:7], v[28:29], 0 op_sel_hi:[1,0]
	v_pk_add_f32 v[4:5], v[30:31], 0 op_sel_hi:[1,0]
	v_cvt_pk_bf16_f32 v6, v6, v7
	v_pk_add_f32 v[2:3], v[2:3], 0 op_sel_hi:[1,0]
	v_cvt_pk_bf16_f32 v7, v4, v5
	global_store_dwordx2 v[36:37], v[6:7], off offset:32
	v_pk_add_f32 v[6:7], v[32:33], 0 op_sel_hi:[1,0]
	v_pk_add_f32 v[4:5], v[34:35], 0 op_sel_hi:[1,0]
	v_cvt_pk_bf16_f32 v6, v6, v7
	v_cvt_pk_bf16_f32 v0, v0, v1
	v_cvt_pk_bf16_f32 v1, v2, v3
	s_nop 0
	v_cvt_pk_bf16_f32 v7, v4, v5
	global_store_dwordx2 v[36:37], v[6:7], off offset:64
	v_pk_add_f32 v[6:7], v[20:21], 0 op_sel_hi:[1,0]
	v_pk_add_f32 v[4:5], v[22:23], 0 op_sel_hi:[1,0]
	v_cvt_pk_bf16_f32 v6, v6, v7
	s_nop 0
	v_cvt_pk_bf16_f32 v7, v4, v5
	global_store_dwordx2 v[36:37], v[6:7], off offset:96
	v_pk_add_f32 v[6:7], v[16:17], 0 op_sel_hi:[1,0]
	v_pk_add_f32 v[4:5], v[18:19], 0 op_sel_hi:[1,0]
	v_cvt_pk_bf16_f32 v6, v6, v7
	s_nop 0
	v_cvt_pk_bf16_f32 v7, v4, v5
	global_store_dwordx2 v[36:37], v[6:7], off offset:128
	v_pk_add_f32 v[6:7], v[12:13], 0 op_sel_hi:[1,0]
	v_pk_add_f32 v[4:5], v[14:15], 0 op_sel_hi:[1,0]
	v_cvt_pk_bf16_f32 v6, v6, v7
	s_nop 0
	v_cvt_pk_bf16_f32 v7, v4, v5
	global_store_dwordx2 v[36:37], v[6:7], off offset:160
	v_pk_add_f32 v[6:7], v[8:9], 0 op_sel_hi:[1,0]
	v_pk_add_f32 v[4:5], v[10:11], 0 op_sel_hi:[1,0]
	v_cvt_pk_bf16_f32 v6, v6, v7
	s_nop 0
	v_cvt_pk_bf16_f32 v7, v4, v5
	global_store_dwordx2 v[36:37], v[6:7], off offset:192
	s_branch .LBB0_1138

; __device__ __forceinline__ unsigned pk2(float lo, float hi) { unsigned r; asm("v_cvt_pk_bf16_f32 %0, %1, %2" : "=v"(r) : "v"(lo), "v"(hi)); return r; }
; __device__ __forceinline__ float bflo(unsigned u) { return __uint_as_float(u << 16); }
; __device__ __forceinline__ float bfhi(unsigned u) { return __uint_as_float(u & 0xffff0000u); }
; __device__ __forceinline__ void conv_rows(const Params& p, const float* cw  ) {
;     ...
;     for (int row = gw; row < MALL; row += NGW) {
;         const int t = row < ML ? (row & (SEQ - 1)) : ((row - ML) & (CTXL - 1)), T = row < ML ? SEQ : CTXL;
;         float a[8];
; #pragma unroll
;         for (int x = 0; x < 8; ++x) a[x] = 0.f;
; #pragma unroll
;         for (int k = 0; k < 3; ++k) {
;             const int tt = t + k - 1;
;             if (tt >= 0 && tt < T) {
;                 const bf16_t* ur = U + (size_t)(row + k - 1) * UEV;
;                 const u32x4 gc = *(const u32x4*)(ur + 512 + lane * 8), xv = *(const u32x4*)(ur + 1024 + lane * 8);
; #pragma unroll
;                 for (int q = 0; q < 4; ++q) { a[2 * q] += w[k][2 * q] * (bflo(gc[q]) * bflo(xv[q])); a[2 * q + 1] += w[k][2 * q + 1] * (bfhi(gc[q]) * bfhi(xv[q])); }
;             }
;         }
;         const u32x4 gb = *(const u32x4*)(U + (size_t)row * UEV + lane * 8);
;         u32x4 o;
; #pragma unroll
;         for (int q = 0; q < 4; ++q) o[q] = pk2(bflo(gb[q]) * a[2 * q], bfhi(gb[q]) * a[2 * q + 1]);
;         *(u32x4*)(MIX + (size_t)row * 1024 + lane * 8) = o;
;     }
.LBB0_1147:
	s_or_b64 exec, exec, s[4:5]
	v_ashrrev_i32_e32 v33, 31, v32
	v_readlane_b32 s2, v254, 31
	s_waitcnt vmcnt(0)
	v_lshlrev_b32_e32 v42, 16, v88
	v_and_b32_e32 v88, 0xffff0000, v88
	v_mul_f32_e32 v0, v0, v42
	v_mul_f32_e32 v1, v1, v88
	v_cvt_pk_bf16_f32 v0, v0, v1
	v_lshlrev_b32_e32 v1, 16, v89
	v_mul_f32_e32 v1, v2, v1
	v_and_b32_e32 v2, 0xffff0000, v89
	v_mul_f32_e32 v2, v3, v2
	v_cvt_pk_bf16_f32 v1, v1, v2
	v_lshlrev_b32_e32 v2, 16, v90
	v_and_b32_e32 v3, 0xffff0000, v90
	v_mul_f32_e32 v2, v4, v2
	v_mul_f32_e32 v3, v5, v3
	v_cvt_pk_bf16_f32 v2, v2, v3
	v_lshlrev_b32_e32 v3, 16, v91
	v_and_b32_e32 v4, 0xffff0000, v91
	v_mul_f32_e32 v3, v6, v3
	v_mul_f32_e32 v4, v7, v4
	v_cvt_pk_bf16_f32 v3, v3, v4
	v_lshlrev_b64 v[4:5], 11, v[32:33]
	v_add_u32_e32 v32, s2, v32
	s_mov_b32 s2, 0x107ff
	v_cmp_lt_i32_e32 vcc, s2, v32
	v_lshl_add_u64 v[4:5], v[36:37], 0, v[4:5]
	s_or_b64 s[0:1], vcc, s[0:1]
	global_store_dwordx4 v[4:5], v[0:3], off
	s_andn2_b64 exec, exec, s[0:1]
	s_cbranch_execz .LBB0_1154
.LBB0_1148:
	s_mov_b32 s2, 0x10000
	v_cmp_gt_i32_e32 vcc, s2, v32
	v_mov_b32_e32 v0, 0xff
	v_mov_b32_e32 v1, 0x100
	v_cndmask_b32_e32 v0, v0, v209, vcc
	v_and_b32_e32 v38, v0, v32
	v_cndmask_b32_e32 v33, v1, v212, vcc
	v_add_u32_e32 v0, -1, v38
	v_mov_b32_e32 v144, v145
	v_cmp_lt_u32_e32 vcc, v0, v33
	v_mov_b32_e32 v146, v145
	v_mov_b32_e32 v147, v145
	v_mov_b32_e32 v148, v145
	v_mov_b32_e32 v149, v145
	v_mov_b32_e32 v150, v145
	v_mov_b32_e32 v151, v145
	v_mov_b64_e32 v[0:1], v[144:145]
	v_mov_b64_e32 v[2:3], v[146:147]
	v_mov_b64_e32 v[4:5], v[148:149]
	v_mov_b64_e32 v[6:7], v[150:151]
	v_add_u32_e32 v92, -1, v32
	s_movk_i32 s2, 0x1400
	v_mad_i64_i32 v[92:93], s[2:3], v92, s2, v[34:35]
	global_load_dwordx4 v[64:67], v[92:93], off offset:1024
	global_load_dwordx4 v[68:71], v[92:93], off offset:2048
	s_movk_i32 s2, 0x1400
	v_mad_i64_i32 v[92:93], s[2:3], v32, s2, v[34:35]
	global_load_dwordx4 v[72:75], v[92:93], off offset:1024
	global_load_dwordx4 v[76:79], v[92:93], off offset:2048
	global_load_dwordx4 v[88:91], v[92:93], off
	v_add_u32_e32 v94, 1, v32
	s_movk_i32 s2, 0x1400
	v_mad_i64_i32 v[94:95], s[2:3], v94, s2, v[34:35]
	global_load_dwordx4 v[80:83], v[94:95], off offset:1024
	global_load_dwordx4 v[84:87], v[94:95], off offset:2048
	s_and_saveexec_b64 s[4:5], vcc
	s_cbranch_execz .LBB0_1150
	s_waitcnt vmcnt(6)
	v_lshlrev_b32_e32 v40, 16, v64
	v_and_b32_e32 v41, 0xffff0000, v64
	s_waitcnt vmcnt(5)
	v_lshlrev_b32_e32 v42, 16, v68
	v_and_b32_e32 v43, 0xffff0000, v68
	v_lshlrev_b32_e32 v64, 16, v65
	v_and_b32_e32 v65, 0xffff0000, v65
	v_lshlrev_b32_e32 v68, 16, v69
	v_and_b32_e32 v69, 0xffff0000, v69
	v_lshlrev_b32_e32 v44, 16, v66
	v_and_b32_e32 v45, 0xffff0000, v66
	v_lshlrev_b32_e32 v46, 16, v70
	v_and_b32_e32 v47, 0xffff0000, v70
	v_lshlrev_b32_e32 v66, 16, v67
	v_lshlrev_b32_e32 v70, 16, v71
	v_and_b32_e32 v71, 0xffff0000, v71
	v_and_b32_e32 v67, 0xffff0000, v67
	v_pk_mul_f32 v[66:67], v[66:67], v[70:71]
	v_pk_mul_f32 v[40:41], v[40:41], v[42:43]
	v_pk_mul_f32 v[64:65], v[64:65], v[68:69]
	v_pk_mul_f32 v[68:69], v[44:45], v[46:47]
	v_pk_fma_f32 v[6:7], v[18:19], v[66:67], 0 op_sel_hi:[1,1,0]
	v_pk_fma_f32 v[4:5], v[16:17], v[68:69], 0 op_sel_hi:[1,1,0]
	v_pk_fma_f32 v[2:3], v[10:11], v[64:65], 0 op_sel_hi:[1,1,0]
	v_pk_fma_f32 v[0:1], v[8:9], v[40:41], 0 op_sel_hi:[1,1,0]
.LBB0_1150:
	s_or_b64 exec, exec, s[4:5]
	v_cmp_lt_u32_e32 vcc, v38, v33
	s_and_saveexec_b64 s[4:5], vcc
	s_cbranch_execz .LBB0_1152
	s_waitcnt vmcnt(4)
	v_lshlrev_b32_e32 v48, 16, v72
	v_and_b32_e32 v49, 0xffff0000, v72
	s_waitcnt vmcnt(3)
	v_lshlrev_b32_e32 v50, 16, v76
	v_and_b32_e32 v51, 0xffff0000, v76
	v_lshlrev_b32_e32 v72, 16, v73
	v_and_b32_e32 v73, 0xffff0000, v73
	v_lshlrev_b32_e32 v76, 16, v77
	v_and_b32_e32 v77, 0xffff0000, v77
	v_lshlrev_b32_e32 v52, 16, v74
	v_and_b32_e32 v53, 0xffff0000, v74
	v_lshlrev_b32_e32 v54, 16, v78
	v_and_b32_e32 v55, 0xffff0000, v78
	v_lshlrev_b32_e32 v74, 16, v75
	v_lshlrev_b32_e32 v78, 16, v79
	v_and_b32_e32 v79, 0xffff0000, v79
	v_and_b32_e32 v75, 0xffff0000, v75
	v_pk_mul_f32 v[74:75], v[74:75], v[78:79]
	v_pk_mul_f32 v[72:73], v[72:73], v[76:77]
	v_pk_mul_f32 v[76:77], v[48:49], v[50:51]
	v_pk_mul_f32 v[78:79], v[52:53], v[54:55]
	v_pk_fma_f32 v[6:7], v[14:15], v[74:75], v[6:7]
	v_pk_fma_f32 v[2:3], v[22:23], v[72:73], v[2:3]
	v_pk_fma_f32 v[4:5], v[12:13], v[78:79], v[4:5]
	v_pk_fma_f32 v[0:1], v[20:21], v[76:77], v[0:1]
.LBB0_1152:
	s_or_b64 exec, exec, s[4:5]
	v_add_u32_e32 v38, 1, v38
	v_cmp_lt_u32_e32 vcc, v38, v33
	s_and_saveexec_b64 s[4:5], vcc
	s_cbranch_execz .LBB0_1147
	s_waitcnt vmcnt(1)
	v_lshlrev_b32_e32 v46, 16, v80
	v_and_b32_e32 v47, 0xffff0000, v80
	s_waitcnt vmcnt(0)
	v_lshlrev_b32_e32 v48, 16, v84
	v_and_b32_e32 v49, 0xffff0000, v84
	v_lshlrev_b32_e32 v80, 16, v81
	v_and_b32_e32 v81, 0xffff0000, v81
	v_lshlrev_b32_e32 v84, 16, v85
	v_and_b32_e32 v85, 0xffff0000, v85
	v_lshlrev_b32_e32 v50, 16, v82
	v_and_b32_e32 v51, 0xffff0000, v82
	v_lshlrev_b32_e32 v52, 16, v86
	v_and_b32_e32 v53, 0xffff0000, v86
	v_lshlrev_b32_e32 v82, 16, v83
	v_lshlrev_b32_e32 v86, 16, v87
	v_and_b32_e32 v87, 0xffff0000, v87
	v_and_b32_e32 v83, 0xffff0000, v83
	v_pk_mul_f32 v[82:83], v[82:83], v[86:87]
	v_pk_mul_f32 v[86:87], v[46:47], v[48:49]
	v_pk_mul_f32 v[80:81], v[80:81], v[84:85]
	v_pk_mul_f32 v[84:85], v[50:51], v[52:53]
	v_pk_fma_f32 v[6:7], v[30:31], v[82:83], v[6:7]
	v_pk_fma_f32 v[4:5], v[28:29], v[84:85], v[4:5]
	v_pk_fma_f32 v[2:3], v[26:27], v[80:81], v[2:3]
	v_pk_fma_f32 v[0:1], v[24:25], v[86:87], v[0:1]
	s_branch .LBB0_1147

; #define LAS __attribute__((address_space(3)))
; __device__ __forceinline__ void dft_item(LAS unsigned char* lds, const bf16_t* F, int KF, const bf16_t* X, int khalf, size_t segoff, size_t kstride, bf16_t* Ob, size_t ostride) {
;     ...
;     for (int kc = 0; kc < KF; kc += 128) {
;         __syncthreads();
; #pragma unroll
;         for (int i = 0; i < 4; ++i) {
;             const int c = tid + 512 * i, k = c >> 4, part = c & 15, kk = kc + k;
;             const u32x4 v = __builtin_nontemporal_load((const u32x4*)(X + (size_t)(kk / khalf) * segoff + (size_t)(kk % khalf) * kstride + part * 8));
;             LAS u32x2* d = (LAS u32x2*)(xs + k * LS + part * 8);
;             d[0] = (u32x2){v.x, v.y}; d[1] = (u32x2){v.z, v.w};
;         }
;         __syncthreads();
; __device__ __forceinline__ void phase_even_b(const Params& p, LAS unsigned char* lds) {
;     ...
;     for (int it = blockIdx.x; it < N3; it += gridDim.x) { const int nc = it & 3, k1 = (it >> 2) & 63, b = it >> 8;
;         dft_item(lds, F3, 256, Z + ((size_t)(b * 64 + k1) * 256) * 512 + nc * 128, 256, 0, 512, MIX + ((size_t)b * SEQ + k1) * 1024 + 512 + nc * 128, (size_t)64 * 1024);
.LBB0_1209:
	v_add_u32_e32 v32, s66, v57
	v_ashrrev_i32_e32 v33, 31, v32
	v_add_u32_sdwa v33, v32, v33 dst_sel:DWORD dst_unused:UNUSED_PAD src0_sel:DWORD src1_sel:BYTE_3
	v_and_b32_e32 v33, 0xffffff00, v33
	v_sub_u32_e32 v32, v32, v33
	v_ashrrev_i32_e32 v33, 31, v32
	v_lshlrev_b64 v[32:33], 10, v[32:33]
	v_lshl_add_u64 v[32:33], v[52:53], 0, v[32:33]
	s_barrier
	global_load_dwordx4 v[96:99], v[32:33], off nt
	v_lshl_add_u64 v[54:55], s[66:67], 1, v[50:51]
	s_and_b64 vcc, exec, s[6:7]
	s_mov_b64 s[6:7], 0
	v_add_u32_e32 v32, s66, v58
	v_ashrrev_i32_e32 v33, 31, v32
	v_add_u32_sdwa v33, v32, v33 dst_sel:DWORD dst_unused:UNUSED_PAD src0_sel:DWORD src1_sel:BYTE_3
	v_and_b32_e32 v33, 0xffffff00, v33
	v_sub_u32_e32 v32, v32, v33
	v_ashrrev_i32_e32 v33, 31, v32
	v_lshlrev_b64 v[32:33], 10, v[32:33]
	v_lshl_add_u64 v[32:33], v[52:53], 0, v[32:33]
	global_load_dwordx4 v[100:103], v[32:33], off nt
	v_add_u32_e32 v32, s66, v59
	v_ashrrev_i32_e32 v33, 31, v32
	v_add_u32_sdwa v33, v32, v33 dst_sel:DWORD dst_unused:UNUSED_PAD src0_sel:DWORD src1_sel:BYTE_3
	v_and_b32_e32 v33, 0xffffff00, v33
	v_sub_u32_e32 v32, v32, v33
	v_ashrrev_i32_e32 v33, 31, v32
	v_lshlrev_b64 v[32:33], 10, v[32:33]
	v_lshl_add_u64 v[32:33], v[52:53], 0, v[32:33]
	global_load_dwordx4 v[104:107], v[32:33], off nt
	v_add_u32_e32 v32, s66, v60
	v_ashrrev_i32_e32 v33, 31, v32
	v_add_u32_sdwa v33, v32, v33 dst_sel:DWORD dst_unused:UNUSED_PAD src0_sel:DWORD src1_sel:BYTE_3
	v_and_b32_e32 v33, 0xffffff00, v33
	v_sub_u32_e32 v32, v32, v33
	v_ashrrev_i32_e32 v33, 31, v32
	v_lshlrev_b64 v[32:33], 10, v[32:33]
	v_lshl_add_u64 v[32:33], v[52:53], 0, v[32:33]
	global_load_dwordx4 v[108:111], v[32:33], off nt
	s_movk_i32 s66, 0x80
	s_waitcnt vmcnt(3)
	ds_write2_b64 v62, v[96:97], v[98:99] offset1:1
	s_waitcnt vmcnt(2)
	ds_write2_b64 v63, v[100:101], v[102:103] offset1:1
	s_waitcnt vmcnt(1)
	ds_write2_b64 v64, v[104:105], v[106:107] offset1:1
	s_waitcnt vmcnt(0)
	ds_write2_b64 v65, v[108:109], v[110:111] offset1:1
	s_waitcnt lgkmcnt(0)
	s_barrier
	global_load_dwordx4 v[32:35], v[54:55], off
	ds_read_u16 v36, v61 offset:264
	ds_read_u16 v37, v61 offset:528
	ds_read_u16 v40, v61 offset:792
	ds_read_u16 v38, v61 offset:1056
	ds_read_u16 v41, v61 offset:1320
	ds_read_u16 v39, v61 offset:1584
	ds_read_u16 v42, v61 offset:1848
	s_waitcnt lgkmcnt(4)
	v_perm_b32 v37, v40, v37, s73
	ds_read_u16 v40, v61
	ds_read_u16 v44, v61 offset:32
	s_waitcnt lgkmcnt(4)
	v_perm_b32 v38, v41, v38, s73
	s_waitcnt lgkmcnt(2)
	v_perm_b32 v39, v42, v39, s73
	s_waitcnt lgkmcnt(1)
	v_perm_b32 v36, v36, v40, s73
	s_waitcnt vmcnt(0)
	s_nop 0
	v_mfma_f32_16x16x32_bf16 v[40:43], v[36:39], v[32:35], v[0:3]
	s_nop 2
	ds_read_u16 v0, v61 offset:296
	ds_read_u16 v1, v61 offset:560
	ds_read_u16 v36, v61 offset:824
	ds_read_u16 v2, v61 offset:1088
	ds_read_u16 v37, v61 offset:1352
	ds_read_u16 v3, v61 offset:1616
	ds_read_u16 v38, v61 offset:1880
	s_waitcnt lgkmcnt(4)
	v_perm_b32 v1, v36, v1, s73
	v_perm_b32 v0, v0, v44, s73
	s_waitcnt lgkmcnt(2)
	v_perm_b32 v2, v37, v2, s73
	s_waitcnt lgkmcnt(0)
	v_perm_b32 v3, v38, v3, s73
	s_nop 1
	v_mfma_f32_16x16x32_bf16 v[0:3], v[0:3], v[32:35], v[16:19]
	s_nop 2
	ds_read_u16 v16, v61 offset:64
	ds_read_u16 v36, v61 offset:328
	ds_read_u16 v17, v61 offset:592
	ds_read_u16 v37, v61 offset:856
	ds_read_u16 v18, v61 offset:1120
	ds_read_u16 v38, v61 offset:1384
	ds_read_u16 v19, v61 offset:1648
	ds_read_u16 v39, v61 offset:1912
	s_waitcnt lgkmcnt(4)
	v_perm_b32 v17, v37, v17, s73
	v_perm_b32 v16, v36, v16, s73
	s_waitcnt lgkmcnt(2)
	v_perm_b32 v18, v38, v18, s73
	s_waitcnt lgkmcnt(0)
	v_perm_b32 v19, v39, v19, s73
	s_nop 1
	v_mfma_f32_16x16x32_bf16 v[4:7], v[16:19], v[32:35], v[4:7]
	ds_read_u16 v16, v61 offset:96
	ds_read_u16 v36, v61 offset:360
	ds_read_u16 v17, v61 offset:624
	ds_read_u16 v37, v61 offset:888
	ds_read_u16 v18, v61 offset:1152
	ds_read_u16 v38, v61 offset:1416
	ds_read_u16 v19, v61 offset:1680
	ds_read_u16 v39, v61 offset:1944
	s_waitcnt lgkmcnt(4)
	v_perm_b32 v17, v37, v17, s73
	v_perm_b32 v16, v36, v16, s73
	s_waitcnt lgkmcnt(2)
	v_perm_b32 v18, v38, v18, s73
	s_waitcnt lgkmcnt(0)
	v_perm_b32 v19, v39, v19, s73
	s_nop 1
	v_mfma_f32_16x16x32_bf16 v[12:15], v[16:19], v[32:35], v[12:15]
	ds_read_u16 v16, v61 offset:128
	ds_read_u16 v36, v61 offset:392
	ds_read_u16 v17, v61 offset:656
	ds_read_u16 v37, v61 offset:920
	ds_read_u16 v18, v61 offset:1184
	ds_read_u16 v38, v61 offset:1448
	ds_read_u16 v19, v61 offset:1712
	ds_read_u16 v39, v61 offset:1976
	s_waitcnt lgkmcnt(4)
	v_perm_b32 v17, v37, v17, s73
	v_perm_b32 v16, v36, v16, s73
	s_waitcnt lgkmcnt(2)
	v_perm_b32 v18, v38, v18, s73
	s_waitcnt lgkmcnt(0)
	v_perm_b32 v19, v39, v19, s73
	s_nop 1
	v_mfma_f32_16x16x32_bf16 v[16:19], v[16:19], v[32:35], v[8:11]
	s_nop 2
	ds_read_u16 v8, v61 offset:160
	ds_read_u16 v36, v61 offset:424
	ds_read_u16 v9, v61 offset:688
	ds_read_u16 v37, v61 offset:952
	ds_read_u16 v10, v61 offset:1216
	ds_read_u16 v38, v61 offset:1480
	ds_read_u16 v11, v61 offset:1744
	ds_read_u16 v39, v61 offset:2008
	s_waitcnt lgkmcnt(4)
	v_perm_b32 v9, v37, v9, s73
	v_perm_b32 v8, v36, v8, s73
	s_waitcnt lgkmcnt(2)
	v_perm_b32 v10, v38, v10, s73
	s_waitcnt lgkmcnt(0)
	v_perm_b32 v11, v39, v11, s73
	s_nop 1
	v_mfma_f32_16x16x32_bf16 v[24:27], v[8:11], v[32:35], v[24:27]
	ds_read_u16 v8, v61 offset:192
	ds_read_u16 v36, v61 offset:456
	ds_read_u16 v9, v61 offset:720
	ds_read_u16 v37, v61 offset:984
	ds_read_u16 v10, v61 offset:1248
	ds_read_u16 v38, v61 offset:1512
	ds_read_u16 v11, v61 offset:1776
	ds_read_u16 v39, v61 offset:2040
	s_waitcnt lgkmcnt(4)
	v_perm_b32 v9, v37, v9, s73
	v_perm_b32 v8, v36, v8, s73
	s_waitcnt lgkmcnt(2)
; #define LAS __attribute__((address_space(3)))
; __device__ __forceinline__ void dft_item(LAS unsigned char* lds, const bf16_t* F, int KF, const bf16_t* X, int khalf, size_t segoff, size_t kstride, bf16_t* Ob, size_t ostride) {
;     ...
; #pragma unroll
;         for (int ks = 0; ks < 4; ++ks) {
;             const bf16x8 af = *(const bf16x8*)(F + (size_t)(16 * w + r16) * KF + kc + 32 * ks + 8 * kq);
; #pragma unroll
;             for (int nt = 0; nt < 8; ++nt) {
;                 LAS const bf16_t* xp = xs + (32 * ks + 8 * kq) * LS + 16 * nt + r16;
;                 bf16x8 bfr;
; #pragma unroll
;                 for (int j = 0; j < 8; ++j) bfr[j] = (short)xp[j * LS];
;                 acc[nt] = __builtin_amdgcn_mfma_f32_16x16x32_bf16(bfr, af, acc[nt], 0, 0, 0);
;             }
;         }
	v_perm_b32 v10, v38, v10, s73
	s_waitcnt lgkmcnt(0)
	v_perm_b32 v11, v39, v11, s73
	s_nop 1
	v_mfma_f32_16x16x32_bf16 v[36:39], v[8:11], v[32:35], v[20:23]
	ds_read_u16 v8, v61 offset:224
	s_nop 1
	ds_read_u16 v20, v61 offset:488
	ds_read_u16 v9, v61 offset:752
	ds_read_u16 v21, v61 offset:1016
	ds_read_u16 v10, v61 offset:1280
	ds_read_u16 v22, v61 offset:1544
	ds_read_u16 v11, v61 offset:1808
	ds_read_u16 v23, v61 offset:2072
	global_load_dwordx4 v[44:47], v[54:55], off offset:64
	s_waitcnt lgkmcnt(4)
	v_perm_b32 v9, v21, v9, s73
	s_waitcnt lgkmcnt(2)
	v_perm_b32 v10, v22, v10, s73
	v_perm_b32 v8, v20, v8, s73
	s_waitcnt lgkmcnt(0)
	v_perm_b32 v11, v23, v11, s73
	s_nop 1
	v_mfma_f32_16x16x32_bf16 v[32:35], v[8:11], v[32:35], v[28:31]
	ds_read_u16 v8, v61 offset:8448
	ds_read_u16 v20, v61 offset:8712
	ds_read_u16 v9, v61 offset:8976
	ds_read_u16 v21, v61 offset:9240
	ds_read_u16 v10, v61 offset:9504
	ds_read_u16 v22, v61 offset:9768
	ds_read_u16 v11, v61 offset:10032
	ds_read_u16 v23, v61 offset:10296
	s_waitcnt lgkmcnt(4)
	v_perm_b32 v9, v21, v9, s73
	v_perm_b32 v8, v20, v8, s73
	s_waitcnt lgkmcnt(2)
	v_perm_b32 v10, v22, v10, s73
	s_waitcnt lgkmcnt(0)
	v_perm_b32 v11, v23, v11, s73
	ds_read_u16 v20, v61 offset:8480
	ds_read_u16 v28, v61 offset:8744
	ds_read_u16 v21, v61 offset:9008
	ds_read_u16 v29, v61 offset:9272
	ds_read_u16 v22, v61 offset:9536
	ds_read_u16 v30, v61 offset:9800
	ds_read_u16 v23, v61 offset:10064
	ds_read_u16 v31, v61 offset:10328
	s_waitcnt lgkmcnt(4)
	v_perm_b32 v21, v29, v21, s73
	v_perm_b32 v20, v28, v20, s73
	s_waitcnt lgkmcnt(2)
	v_perm_b32 v22, v30, v22, s73
	s_waitcnt vmcnt(0)
	v_mfma_f32_16x16x32_bf16 v[8:11], v[8:11], v[44:47], v[40:43]
	s_waitcnt lgkmcnt(0)
	v_perm_b32 v23, v31, v23, s73
	s_nop 1
	v_mfma_f32_16x16x32_bf16 v[0:3], v[20:23], v[44:47], v[0:3]
	ds_read_u16 v20, v61 offset:8512
	ds_read_u16 v28, v61 offset:8776
	ds_read_u16 v21, v61 offset:9040
	ds_read_u16 v29, v61 offset:9304
	ds_read_u16 v22, v61 offset:9568
	ds_read_u16 v30, v61 offset:9832
	ds_read_u16 v23, v61 offset:10096
	ds_read_u16 v31, v61 offset:10360
	s_waitcnt lgkmcnt(4)
	v_perm_b32 v21, v29, v21, s73
	v_perm_b32 v20, v28, v20, s73
	s_waitcnt lgkmcnt(2)
	v_perm_b32 v22, v30, v22, s73
	s_waitcnt lgkmcnt(0)
	v_perm_b32 v23, v31, v23, s73
	s_nop 1
	v_mfma_f32_16x16x32_bf16 v[4:7], v[20:23], v[44:47], v[4:7]
	ds_read_u16 v20, v61 offset:8544
	ds_read_u16 v28, v61 offset:8808
	ds_read_u16 v21, v61 offset:9072
	ds_read_u16 v29, v61 offset:9336
	ds_read_u16 v22, v61 offset:9600
	ds_read_u16 v30, v61 offset:9864
	ds_read_u16 v23, v61 offset:10128
	ds_read_u16 v31, v61 offset:10392
	s_waitcnt lgkmcnt(4)
	v_perm_b32 v21, v29, v21, s73
	v_perm_b32 v20, v28, v20, s73
	s_waitcnt lgkmcnt(2)
	v_perm_b32 v22, v30, v22, s73
	s_waitcnt lgkmcnt(0)
	v_perm_b32 v23, v31, v23, s73
	s_nop 1
	v_mfma_f32_16x16x32_bf16 v[12:15], v[20:23], v[44:47], v[12:15]
	ds_read_u16 v20, v61 offset:8576
	ds_read_u16 v28, v61 offset:8840
	ds_read_u16 v21, v61 offset:9104
	ds_read_u16 v29, v61 offset:9368
	ds_read_u16 v22, v61 offset:9632
	ds_read_u16 v30, v61 offset:9896
	ds_read_u16 v23, v61 offset:10160
	ds_read_u16 v31, v61 offset:10424
	s_waitcnt lgkmcnt(4)
	v_perm_b32 v21, v29, v21, s73
	v_perm_b32 v20, v28, v20, s73
	s_waitcnt lgkmcnt(2)
	v_perm_b32 v22, v30, v22, s73
	s_waitcnt lgkmcnt(0)
	v_perm_b32 v23, v31, v23, s73
	s_nop 1
	v_mfma_f32_16x16x32_bf16 v[20:23], v[20:23], v[44:47], v[16:19]
	s_nop 2
	ds_read_u16 v16, v61 offset:8608
	ds_read_u16 v28, v61 offset:8872
	ds_read_u16 v17, v61 offset:9136
	ds_read_u16 v29, v61 offset:9400
	ds_read_u16 v18, v61 offset:9664
	ds_read_u16 v30, v61 offset:9928
	ds_read_u16 v19, v61 offset:10192
	ds_read_u16 v31, v61 offset:10456
	s_waitcnt lgkmcnt(4)
	v_perm_b32 v17, v29, v17, s73
	v_perm_b32 v16, v28, v16, s73
	s_waitcnt lgkmcnt(2)
	v_perm_b32 v18, v30, v18, s73
	s_waitcnt lgkmcnt(0)
	v_perm_b32 v19, v31, v19, s73
	s_nop 1
	v_mfma_f32_16x16x32_bf16 v[24:27], v[16:19], v[44:47], v[24:27]
	ds_read_u16 v16, v61 offset:8640
	ds_read_u16 v28, v61 offset:8904
	ds_read_u16 v17, v61 offset:9168
	ds_read_u16 v29, v61 offset:9432
	ds_read_u16 v18, v61 offset:9696
	ds_read_u16 v30, v61 offset:9960
	ds_read_u16 v19, v61 offset:10224
	ds_read_u16 v31, v61 offset:10488
	s_waitcnt lgkmcnt(4)
	v_perm_b32 v17, v29, v17, s73
	v_perm_b32 v16, v28, v16, s73
	s_waitcnt lgkmcnt(2)
	v_perm_b32 v18, v30, v18, s73
	s_waitcnt lgkmcnt(0)
	v_perm_b32 v19, v31, v19, s73
	s_nop 1
	v_mfma_f32_16x16x32_bf16 v[28:31], v[16:19], v[44:47], v[36:39]
	ds_read_u16 v16, v61 offset:8672
	s_nop 1
	ds_read_u16 v36, v61 offset:8936
	ds_read_u16 v17, v61 offset:9200
	ds_read_u16 v37, v61 offset:9464
	ds_read_u16 v18, v61 offset:9728
	ds_read_u16 v38, v61 offset:9992
	ds_read_u16 v19, v61 offset:10256
	ds_read_u16 v39, v61 offset:10520
	global_load_dwordx4 v[40:43], v[54:55], off offset:128
	s_waitcnt lgkmcnt(4)
	v_perm_b32 v17, v37, v17, s73
	s_waitcnt lgkmcnt(2)
	v_perm_b32 v18, v38, v18, s73
	v_perm_b32 v16, v36, v16, s73
	s_waitcnt lgkmcnt(0)
	v_perm_b32 v19, v39, v19, s73
	s_nop 1
	v_mfma_f32_16x16x32_bf16 v[32:35], v[16:19], v[44:47], v[32:35]
	ds_read_u16 v16, v61 offset:16896
	ds_read_u16 v36, v61 offset:17160
	ds_read_u16 v17, v61 offset:17424
	ds_read_u16 v37, v61 offset:17688
	ds_read_u16 v18, v61 offset:17952
	ds_read_u16 v38, v61 offset:18216
	ds_read_u16 v19, v61 offset:18480
	ds_read_u16 v39, v61 offset:18744
	s_waitcnt lgkmcnt(4)
	v_perm_b32 v17, v37, v17, s73
	v_perm_b32 v16, v36, v16, s73
	s_waitcnt lgkmcnt(2)
	v_perm_b32 v18, v38, v18, s73
	s_waitcnt lgkmcnt(0)
	v_perm_b32 v19, v39, v19, s73
	s_waitcnt vmcnt(0)
; #define LAS __attribute__((address_space(3)))
; __device__ __forceinline__ void dft_item(LAS unsigned char* lds, const bf16_t* F, int KF, const bf16_t* X, int khalf, size_t segoff, size_t kstride, bf16_t* Ob, size_t ostride) {
;     ...
; #pragma unroll
;         for (int ks = 0; ks < 4; ++ks) {
;             const bf16x8 af = *(const bf16x8*)(F + (size_t)(16 * w + r16) * KF + kc + 32 * ks + 8 * kq);
; #pragma unroll
;             for (int nt = 0; nt < 8; ++nt) {
;                 LAS const bf16_t* xp = xs + (32 * ks + 8 * kq) * LS + 16 * nt + r16;
;                 bf16x8 bfr;
; #pragma unroll
;                 for (int j = 0; j < 8; ++j) bfr[j] = (short)xp[j * LS];
;                 acc[nt] = __builtin_amdgcn_mfma_f32_16x16x32_bf16(bfr, af, acc[nt], 0, 0, 0);
;             }
;         }
	s_nop 0
	v_mfma_f32_16x16x32_bf16 v[36:39], v[16:19], v[40:43], v[8:11]
	s_nop 2
	ds_read_u16 v8, v61 offset:16928
	ds_read_u16 v16, v61 offset:17192
	ds_read_u16 v9, v61 offset:17456
	ds_read_u16 v17, v61 offset:17720
	ds_read_u16 v10, v61 offset:17984
	ds_read_u16 v18, v61 offset:18248
	ds_read_u16 v11, v61 offset:18512
	ds_read_u16 v19, v61 offset:18776
	s_waitcnt lgkmcnt(4)
	v_perm_b32 v9, v17, v9, s73
	v_perm_b32 v8, v16, v8, s73
	s_waitcnt lgkmcnt(2)
	v_perm_b32 v10, v18, v10, s73
	s_waitcnt lgkmcnt(0)
	v_perm_b32 v11, v19, v11, s73
	s_nop 1
	v_mfma_f32_16x16x32_bf16 v[16:19], v[8:11], v[40:43], v[0:3]
	s_nop 2
	ds_read_u16 v0, v61 offset:16960
	ds_read_u16 v8, v61 offset:17224
	ds_read_u16 v1, v61 offset:17488
	ds_read_u16 v9, v61 offset:17752
	ds_read_u16 v2, v61 offset:18016
	ds_read_u16 v10, v61 offset:18280
	ds_read_u16 v3, v61 offset:18544
	ds_read_u16 v11, v61 offset:18808
	s_waitcnt lgkmcnt(4)
	v_perm_b32 v1, v9, v1, s73
	v_perm_b32 v0, v8, v0, s73
	s_waitcnt lgkmcnt(2)
	v_perm_b32 v2, v10, v2, s73
	s_waitcnt lgkmcnt(0)
	v_perm_b32 v3, v11, v3, s73
	s_nop 1
	v_mfma_f32_16x16x32_bf16 v[4:7], v[0:3], v[40:43], v[4:7]
	ds_read_u16 v0, v61 offset:16992
	ds_read_u16 v8, v61 offset:17256
	ds_read_u16 v1, v61 offset:17520
	ds_read_u16 v9, v61 offset:17784
	ds_read_u16 v2, v61 offset:18048
	ds_read_u16 v10, v61 offset:18312
	ds_read_u16 v3, v61 offset:18576
	ds_read_u16 v11, v61 offset:18840
	s_waitcnt lgkmcnt(4)
	v_perm_b32 v1, v9, v1, s73
	v_perm_b32 v0, v8, v0, s73
	s_waitcnt lgkmcnt(2)
	v_perm_b32 v2, v10, v2, s73
	s_waitcnt lgkmcnt(0)
	v_perm_b32 v3, v11, v3, s73
	s_nop 1
	v_mfma_f32_16x16x32_bf16 v[12:15], v[0:3], v[40:43], v[12:15]
	ds_read_u16 v0, v61 offset:17024
	ds_read_u16 v8, v61 offset:17288
	ds_read_u16 v1, v61 offset:17552
	ds_read_u16 v9, v61 offset:17816
	ds_read_u16 v2, v61 offset:18080
	ds_read_u16 v10, v61 offset:18344
	ds_read_u16 v3, v61 offset:18608
	ds_read_u16 v11, v61 offset:18872
	s_waitcnt lgkmcnt(4)
	v_perm_b32 v1, v9, v1, s73
	v_perm_b32 v0, v8, v0, s73
	s_waitcnt lgkmcnt(2)
	v_perm_b32 v2, v10, v2, s73
	s_waitcnt lgkmcnt(0)
	v_perm_b32 v3, v11, v3, s73
	s_nop 1
	v_mfma_f32_16x16x32_bf16 v[8:11], v[0:3], v[40:43], v[20:23]
	ds_read_u16 v0, v61 offset:17056
	s_nop 1
	ds_read_u16 v20, v61 offset:17320
	ds_read_u16 v1, v61 offset:17584
	ds_read_u16 v21, v61 offset:17848
	ds_read_u16 v2, v61 offset:18112
	ds_read_u16 v22, v61 offset:18376
	ds_read_u16 v3, v61 offset:18640
	ds_read_u16 v23, v61 offset:18904
	s_waitcnt lgkmcnt(4)
	v_perm_b32 v1, v21, v1, s73
	v_perm_b32 v0, v20, v0, s73
	s_waitcnt lgkmcnt(2)
	v_perm_b32 v2, v22, v2, s73
	s_waitcnt lgkmcnt(0)
	v_perm_b32 v3, v23, v3, s73
	s_nop 1
	v_mfma_f32_16x16x32_bf16 v[24:27], v[0:3], v[40:43], v[24:27]
	ds_read_u16 v0, v61 offset:17088
	ds_read_u16 v20, v61 offset:17352
	ds_read_u16 v1, v61 offset:17616
	ds_read_u16 v21, v61 offset:17880
	ds_read_u16 v2, v61 offset:18144
	ds_read_u16 v22, v61 offset:18408
	ds_read_u16 v3, v61 offset:18672
	ds_read_u16 v23, v61 offset:18936
	s_waitcnt lgkmcnt(4)
	v_perm_b32 v1, v21, v1, s73
	v_perm_b32 v0, v20, v0, s73
	s_waitcnt lgkmcnt(2)
	v_perm_b32 v2, v22, v2, s73
	s_waitcnt lgkmcnt(0)
	v_perm_b32 v3, v23, v3, s73
	s_nop 1
	v_mfma_f32_16x16x32_bf16 v[20:23], v[0:3], v[40:43], v[28:31]
	ds_read_u16 v0, v61 offset:17120
	s_nop 1
	ds_read_u16 v28, v61 offset:17384
	ds_read_u16 v1, v61 offset:17648
	ds_read_u16 v29, v61 offset:17912
	ds_read_u16 v2, v61 offset:18176
	ds_read_u16 v30, v61 offset:18440
	ds_read_u16 v3, v61 offset:18704
	ds_read_u16 v31, v61 offset:18968
	s_waitcnt lgkmcnt(4)
	v_perm_b32 v1, v29, v1, s73
	v_perm_b32 v0, v28, v0, s73
	s_waitcnt lgkmcnt(2)
	v_perm_b32 v2, v30, v2, s73
	s_waitcnt lgkmcnt(0)
	v_perm_b32 v3, v31, v3, s73
	s_nop 1
	v_mfma_f32_16x16x32_bf16 v[28:31], v[0:3], v[40:43], v[32:35]
	s_nop 2
	global_load_dwordx4 v[32:35], v[54:55], off offset:192
	ds_read_u16 v0, v61 offset:25344
	ds_read_u16 v40, v61 offset:25608
	ds_read_u16 v1, v61 offset:25872
	ds_read_u16 v41, v61 offset:26136
	ds_read_u16 v2, v61 offset:26400
	ds_read_u16 v42, v61 offset:26664
	ds_read_u16 v3, v61 offset:26928
	ds_read_u16 v43, v61 offset:27192
	s_waitcnt lgkmcnt(4)
	v_perm_b32 v1, v41, v1, s73
	v_perm_b32 v0, v40, v0, s73
	s_waitcnt lgkmcnt(2)
	v_perm_b32 v2, v42, v2, s73
	s_waitcnt lgkmcnt(0)
	v_perm_b32 v3, v43, v3, s73
	s_waitcnt vmcnt(0)
	s_nop 0
	v_mfma_f32_16x16x32_bf16 v[0:3], v[0:3], v[32:35], v[36:39]
	s_nop 2
	ds_read_u16 v36, v61 offset:25376
	ds_read_u16 v40, v61 offset:25640
	ds_read_u16 v37, v61 offset:25904
	ds_read_u16 v41, v61 offset:26168
	ds_read_u16 v38, v61 offset:26432
	ds_read_u16 v42, v61 offset:26696
	ds_read_u16 v39, v61 offset:26960
	ds_read_u16 v43, v61 offset:27224
	s_waitcnt lgkmcnt(4)
	v_perm_b32 v37, v41, v37, s73
	v_perm_b32 v36, v40, v36, s73
	s_waitcnt lgkmcnt(2)
	v_perm_b32 v38, v42, v38, s73
	s_waitcnt lgkmcnt(0)
	v_perm_b32 v39, v43, v39, s73
	s_nop 1
	v_mfma_f32_16x16x32_bf16 v[16:19], v[36:39], v[32:35], v[16:19]
	ds_read_u16 v36, v61 offset:25408
	ds_read_u16 v40, v61 offset:25672
	ds_read_u16 v37, v61 offset:25936
	ds_read_u16 v41, v61 offset:26200
	ds_read_u16 v38, v61 offset:26464
	ds_read_u16 v42, v61 offset:26728
	ds_read_u16 v39, v61 offset:26992
	ds_read_u16 v43, v61 offset:27256
	s_waitcnt lgkmcnt(4)
	v_perm_b32 v37, v41, v37, s73
	v_perm_b32 v36, v40, v36, s73
	s_waitcnt lgkmcnt(2)
; __device__ __forceinline__ unsigned pk2(float lo, float hi) { unsigned r; asm("v_cvt_pk_bf16_f32 %0, %1, %2" : "=v"(r) : "v"(lo), "v"(hi)); return r; }
; __device__ __forceinline__ void dft_item(LAS unsigned char* lds, const bf16_t* F, int KF, const bf16_t* X, int khalf, size_t segoff, size_t kstride, bf16_t* Ob, size_t ostride) {
;     ...
; #pragma unroll
;     for (int nt = 0; nt < 8; ++nt) {
;         const f32x4 v = acc[nt] + 0.f;
;         u32x2 o; o.x = pk2(v[0], v[1]); o.y = pk2(v[2], v[3]);
;         *(u32x2*)(Ob + (size_t)(16 * w + r16) * ostride + 16 * nt + 4 * kq) = o;
;     }
; __device__ __forceinline__ void phase_even_b(const Params& p, LAS unsigned char* lds) {
;     ...
;     for (int it = blockIdx.x; it < N3; it += gridDim.x) { const int nc = it & 3, k1 = (it >> 2) & 63, b = it >> 8;
;         dft_item(lds, F3, 256, Z + ((size_t)(b * 64 + k1) * 256) * 512 + nc * 128, 256, 0, 512, MIX + ((size_t)b * SEQ + k1) * 1024 + 512 + nc * 128, (size_t)64 * 1024);
;     }
	v_perm_b32 v38, v42, v38, s73
	s_waitcnt lgkmcnt(0)
	v_perm_b32 v39, v43, v39, s73
	s_nop 1
	v_mfma_f32_16x16x32_bf16 v[4:7], v[36:39], v[32:35], v[4:7]
	ds_read_u16 v36, v61 offset:25440
	ds_read_u16 v40, v61 offset:25704
	ds_read_u16 v37, v61 offset:25968
	ds_read_u16 v41, v61 offset:26232
	ds_read_u16 v38, v61 offset:26496
	ds_read_u16 v42, v61 offset:26760
	ds_read_u16 v39, v61 offset:27024
	ds_read_u16 v43, v61 offset:27288
	s_waitcnt lgkmcnt(4)
	v_perm_b32 v37, v41, v37, s73
	v_perm_b32 v36, v40, v36, s73
	s_waitcnt lgkmcnt(2)
	v_perm_b32 v38, v42, v38, s73
	s_waitcnt lgkmcnt(0)
	v_perm_b32 v39, v43, v39, s73
	s_nop 1
	v_mfma_f32_16x16x32_bf16 v[12:15], v[36:39], v[32:35], v[12:15]
	ds_read_u16 v36, v61 offset:25472
	ds_read_u16 v40, v61 offset:25736
	ds_read_u16 v37, v61 offset:26000
	ds_read_u16 v41, v61 offset:26264
	ds_read_u16 v38, v61 offset:26528
	ds_read_u16 v42, v61 offset:26792
	ds_read_u16 v39, v61 offset:27056
	ds_read_u16 v43, v61 offset:27320
	s_waitcnt lgkmcnt(4)
	v_perm_b32 v37, v41, v37, s73
	v_perm_b32 v36, v40, v36, s73
	s_waitcnt lgkmcnt(2)
	v_perm_b32 v38, v42, v38, s73
	s_waitcnt lgkmcnt(0)
	v_perm_b32 v39, v43, v39, s73
	s_nop 1
	v_mfma_f32_16x16x32_bf16 v[8:11], v[36:39], v[32:35], v[8:11]
	ds_read_u16 v36, v61 offset:25504
	ds_read_u16 v40, v61 offset:25768
	ds_read_u16 v37, v61 offset:26032
	ds_read_u16 v41, v61 offset:26296
	ds_read_u16 v38, v61 offset:26560
	ds_read_u16 v42, v61 offset:26824
	ds_read_u16 v39, v61 offset:27088
	ds_read_u16 v43, v61 offset:27352
	s_waitcnt lgkmcnt(4)
	v_perm_b32 v37, v41, v37, s73
	v_perm_b32 v36, v40, v36, s73
	s_waitcnt lgkmcnt(2)
	v_perm_b32 v38, v42, v38, s73
	s_waitcnt lgkmcnt(0)
	v_perm_b32 v39, v43, v39, s73
	s_nop 1
	v_mfma_f32_16x16x32_bf16 v[24:27], v[36:39], v[32:35], v[24:27]
	ds_read_u16 v36, v61 offset:25536
	ds_read_u16 v40, v61 offset:25800
	ds_read_u16 v37, v61 offset:26064
	ds_read_u16 v41, v61 offset:26328
	ds_read_u16 v38, v61 offset:26592
	ds_read_u16 v42, v61 offset:26856
	ds_read_u16 v39, v61 offset:27120
	ds_read_u16 v43, v61 offset:27384
	s_waitcnt lgkmcnt(4)
	v_perm_b32 v37, v41, v37, s73
	v_perm_b32 v36, v40, v36, s73
	s_waitcnt lgkmcnt(2)
	v_perm_b32 v38, v42, v38, s73
	s_waitcnt lgkmcnt(0)
	v_perm_b32 v39, v43, v39, s73
	s_nop 1
	v_mfma_f32_16x16x32_bf16 v[20:23], v[36:39], v[32:35], v[20:23]
	ds_read_u16 v36, v61 offset:25568
	ds_read_u16 v40, v61 offset:25832
	ds_read_u16 v37, v61 offset:26096
	ds_read_u16 v41, v61 offset:26360
	ds_read_u16 v38, v61 offset:26624
	ds_read_u16 v42, v61 offset:26888
	ds_read_u16 v39, v61 offset:27152
	ds_read_u16 v43, v61 offset:27416
	s_waitcnt lgkmcnt(4)
	v_perm_b32 v37, v41, v37, s73
	v_perm_b32 v36, v40, v36, s73
	s_waitcnt lgkmcnt(2)
	v_perm_b32 v38, v42, v38, s73
	s_waitcnt lgkmcnt(0)
	v_perm_b32 v39, v43, v39, s73
	s_nop 1
	v_mfma_f32_16x16x32_bf16 v[28:31], v[36:39], v[32:35], v[28:31]
	s_cbranch_vccnz .LBB0_1209
	s_ashr_i32 s5, s4, 31
	s_lshl_b64 s[4:5], s[4:5], 24
	s_add_u32 s4, s2, s4
	s_addc_u32 s5, s3, s5
	s_lshl_b32 s6, s11, 11
	s_add_u32 s4, s4, s6
	s_addc_u32 s5, s5, 0
	s_lshl_b32 s6, s12, 1
	s_add_u32 s4, s4, s6
	s_addc_u32 s5, s5, 0
	v_lshlrev_b64 v[32:33], 17, v[48:49]
	v_lshl_add_u64 v[32:33], s[4:5], 0, v[32:33]
	v_lshlrev_b32_e32 v144, 3, v56
	v_lshl_add_u64 v[32:33], v[32:33], 0, v[144:145]
	s_mov_b64 s[4:5], 0x304d8b00
	v_lshl_add_u64 v[34:35], v[32:33], 0, s[4:5]
	v_pk_add_f32 v[2:3], v[2:3], 0 op_sel_hi:[1,0]
	v_pk_add_f32 v[0:1], v[0:1], 0 op_sel_hi:[1,0]
	s_mov_b32 s4, 0x304d8000
	v_cvt_pk_bf16_f32 v0, v0, v1
	v_cvt_pk_bf16_f32 v1, v2, v3
	v_add_co_u32_e32 v2, vcc, s4, v32
	v_readlane_b32 s4, v254, 4
	s_nop 0
	v_addc_co_u32_e32 v3, vcc, 0, v33, vcc
	global_store_dwordx2 v[2:3], v[0:1], off offset:2816
	v_pk_add_f32 v[2:3], v[16:17], 0 op_sel_hi:[1,0]
	v_pk_add_f32 v[0:1], v[18:19], 0 op_sel_hi:[1,0]
	v_cvt_pk_bf16_f32 v2, v2, v3
	s_add_i32 s10, s10, s4
	v_cvt_pk_bf16_f32 v3, v0, v1
	global_store_dwordx2 v[34:35], v[2:3], off offset:32
	v_pk_add_f32 v[2:3], v[4:5], 0 op_sel_hi:[1,0]
	v_pk_add_f32 v[0:1], v[6:7], 0 op_sel_hi:[1,0]
	v_cvt_pk_bf16_f32 v2, v2, v3
	s_cmpk_lt_i32 s10, 0x800
	v_cvt_pk_bf16_f32 v3, v0, v1
	global_store_dwordx2 v[34:35], v[2:3], off offset:64
	v_pk_add_f32 v[2:3], v[12:13], 0 op_sel_hi:[1,0]
	v_pk_add_f32 v[0:1], v[14:15], 0 op_sel_hi:[1,0]
	v_cvt_pk_bf16_f32 v2, v2, v3
	v_readlane_b32 s5, v254, 5
	v_cvt_pk_bf16_f32 v3, v0, v1
	global_store_dwordx2 v[34:35], v[2:3], off offset:96
	v_pk_add_f32 v[2:3], v[8:9], 0 op_sel_hi:[1,0]
	v_pk_add_f32 v[0:1], v[10:11], 0 op_sel_hi:[1,0]
	v_cvt_pk_bf16_f32 v2, v2, v3
	s_nop 0
	v_cvt_pk_bf16_f32 v3, v0, v1
	global_store_dwordx2 v[34:35], v[2:3], off offset:128
	v_pk_add_f32 v[2:3], v[24:25], 0 op_sel_hi:[1,0]
	v_pk_add_f32 v[0:1], v[26:27], 0 op_sel_hi:[1,0]
	v_cvt_pk_bf16_f32 v2, v2, v3
	s_nop 0
	v_cvt_pk_bf16_f32 v3, v0, v1
	global_store_dwordx2 v[34:35], v[2:3], off offset:160
	v_pk_add_f32 v[2:3], v[20:21], 0 op_sel_hi:[1,0]
	v_pk_add_f32 v[0:1], v[22:23], 0 op_sel_hi:[1,0]
	v_cvt_pk_bf16_f32 v2, v2, v3
	s_nop 0
	v_cvt_pk_bf16_f32 v3, v0, v1
	global_store_dwordx2 v[34:35], v[2:3], off offset:192
	v_pk_add_f32 v[2:3], v[28:29], 0 op_sel_hi:[1,0]
	v_pk_add_f32 v[0:1], v[30:31], 0 op_sel_hi:[1,0]
	v_cvt_pk_bf16_f32 v2, v2, v3
	s_nop 0
	v_cvt_pk_bf16_f32 v3, v0, v1
	global_store_dwordx2 v[34:35], v[2:3], off offset:224
	s_cbranch_scc1 .LBB0_1208
